# static s_setprio 1 for waves 4-7 during the attention units
# speedup vs baseline: 1.0031x; 1.0031x over previous
; __device__ __forceinline__ bool attn_unit(const Ptrs& P, LAS unsigned char* lds, int unit, int tid, int wave, int lane, bool pre, int nxt) {
;     ...
;     const int g = wave & 3, q0 = 64 * (wave >> 2), h = kh * 4 + g, r = lane & 31, hh = lane >> 5;
;     unsigned char* ws = P.ws;
;     bf16_t* Qb = (bf16_t*)(ws + WS_Q) + (size_t)(b * SEQ + n * 128 + q0) * DM + h * 64;
;     const bf16_t* Kg = (const bf16_t*)(ws + WS_K) + (size_t)b * SEQ * KVW + kh * 64; const bf16_t* Vg = (const bf16_t*)(ws + WS_VT) + (size_t)(b * 4 + kh) * 64 * SEQ;
;     const bf16_t* Kcg = (const bf16_t*)(ws + WS_KC) + (size_t)b * CTX * KVW + kh * 64; const bf16_t* Vcg = (const bf16_t*)(ws + WS_VCT) + (size_t)(b * 4 + kh) * 64 * CTX;
;     float mq = fabsf(P.qg[lane]), mk = fabsf(P.kg[lane]);
; #pragma unroll
;     for (int o = 1; o < 64; o <<= 1) { mq = fmaxf(mq, __shfl_xor(mq, o)); mk = fmaxf(mk, __shfl_xor(mk, o)); }
;     const float sink2 = P.sink[h] * LOG2E; const float mshift = fmaxf(64.0f * QSCALE * mq * mk, sink2);
;     bf16x8_t qf[2][4];
; #pragma unroll
;     for (int cb = 0; cb < 2; ++cb)
; #pragma unroll
;         for (int ds = 0; ds < 4; ++ds) qf[cb][ds] = __builtin_nontemporal_load((const bf16x8_t*)(Qb + (size_t)(32 * cb + r) * DM + 16 * ds + 8 * hh));
;     f32x16 o[2][2];
; #pragma unroll
;     for (int db = 0; db < 2; ++db)
; #pragma unroll
;         for (int cb = 0; cb < 2; ++cb)
; #pragma unroll
;             for (int i = 0; i < 16; ++i) o[db][cb][i] = 0.f;
;     float rs[2] = {0.f, 0.f};
;     f32x16 negm;
; #pragma unroll
;     for (int i = 0; i < 16; ++i) negm[i] = -mshift;
; __device__ __forceinline__ void mk_p3(const Ptrs& P, LAS unsigned char* lds, int tid, int wave, int lane, int bx, int G, bool dry) {
;     ...
;         { bool pre = false; for (int u = bx; u < NB * 32 * 4; u += G) pre = attn_unit(P, lds, u, tid, wave, lane, pre, u + G < NB * 32 * 4 ? u + G : -1); }
.LBB9_305:
	s_cmp_lt_i32 s92, 4
	s_cselect_b64 s[2:3], -1, 0
	s_and_b64 s[22:23], s[2:3], s[0:1]
	s_andn2_b64 vcc, exec, s[22:23]
	s_cbranch_vccnz .LBB9_444
	v_writelane_b32 v251, s22, 33
	s_cmpk_gt_i32 s97, 0x1ff
	v_and_b32_e32 v171, 31, v208
	v_writelane_b32 v251, s23, 34
	v_writelane_b32 v251, s80, 35
	v_lshrrev_b32_e32 v184, 5, v170
	s_nop 0
	v_writelane_b32 v251, s81, 36
	v_writelane_b32 v251, s96, 37
	v_writelane_b32 v251, s83, 38
	v_writelane_b32 v251, s97, 39
	s_cbranch_scc1 .LBB9_413
	s_cmp_lt_u32 s50, 4
	s_cbranch_scc1 .Lprio_lo
	s_setprio 1
.Lprio_lo:
	v_mbcnt_lo_u32_b32 v0, -1, 0
	v_mbcnt_hi_u32_b32 v0, -1, v0
	v_and_b32_e32 v1, 64, v0
	v_add_u32_e32 v1, 64, v1
	v_xor_b32_e32 v2, 1, v0
	v_cmp_lt_i32_e32 vcc, v2, v1
	s_bfe_u32 s0, s40, 0x20006
	v_writelane_b32 v251, s0, 40
	v_cndmask_b32_e32 v2, v0, v2, vcc
	v_lshlrev_b32_e32 v185, 2, v2
	v_xor_b32_e32 v2, 2, v0
	v_cmp_lt_i32_e32 vcc, v2, v1
	s_lshl_b32 s0, s50, 4
	s_and_b32 s33, s0, 0x3fffffc0
	v_cndmask_b32_e32 v2, v0, v2, vcc
	v_lshlrev_b32_e32 v186, 2, v2
	v_xor_b32_e32 v2, 4, v0
	v_cmp_lt_i32_e32 vcc, v2, v1
	s_cmpk_lt_u32 s40, 0x8c0
	s_cselect_b64 s[54:55], -1, 0
	v_cndmask_b32_e32 v2, v0, v2, vcc
	v_lshlrev_b32_e32 v187, 2, v2
	v_xor_b32_e32 v2, 8, v0
	v_cmp_lt_i32_e32 vcc, v2, v1
	s_or_b32 s2, s0, 63
	s_or_b32 s3, s33, 32
	v_cndmask_b32_e32 v2, v0, v2, vcc
	v_lshlrev_b32_e32 v188, 2, v2
	v_xor_b32_e32 v2, 16, v0
	v_cmp_lt_i32_e32 vcc, v2, v1
	v_or_b32_e32 v5, 32, v170
	v_lshlrev_b32_e32 v191, 4, v184
	v_cndmask_b32_e32 v2, v0, v2, vcc
	v_lshlrev_b32_e32 v189, 2, v2
	v_xor_b32_e32 v2, 32, v0
	v_cmp_lt_i32_e32 vcc, v2, v1
	v_mov_b32_e32 v1, 0
	v_mul_u32_u24_e32 v6, 0x110, v5
	v_cndmask_b32_e32 v0, v0, v2, vcc
	v_lshlrev_b32_e32 v190, 2, v0
	v_lshlrev_b32_e32 v0, 2, v184
	v_sub_u32_e32 v0, v171, v0
	v_cmp_lt_i32_e64 s[36:37], 10, v0
	v_cmp_gt_i32_e64 s[0:1], 1, v0
	v_cmp_gt_i32_e64 s[4:5], 2, v0
	v_writelane_b32 v251, s36, 41
	v_cmp_gt_i32_e64 s[6:7], 3, v0
	v_cmp_gt_i32_e64 s[8:9], 4, v0
	v_writelane_b32 v251, s37, 42
	v_cmp_lt_i32_e64 s[36:37], 15, v0
	v_cmp_gt_i32_e64 s[10:11], 9, v0
	v_cmp_gt_i32_e64 s[12:13], 10, v0
	v_writelane_b32 v251, s36, 43
	v_cmp_gt_i32_e64 s[14:15], 11, v0
	v_cmp_gt_i32_e64 s[16:17], 12, v0
	v_writelane_b32 v251, s37, 44
	v_cmp_lt_i32_e64 s[36:37], 16, v0
	v_cmp_gt_i32_e64 s[18:19], 17, v0
	v_cmp_gt_i32_e64 s[20:21], 18, v0
	v_writelane_b32 v251, s36, 45
	v_cmp_gt_i32_e64 s[22:23], 19, v0
	v_cmp_gt_i32_e64 s[24:25], 20, v0
	v_writelane_b32 v251, s37, 46
	v_cmp_lt_i32_e64 s[36:37], 17, v0
	v_cmp_gt_i32_e64 s[26:27], 25, v0
	v_cmp_gt_i32_e64 s[28:29], 26, v0
	v_writelane_b32 v251, s36, 47
	v_cmp_gt_i32_e64 s[30:31], 27, v0
	v_cmp_gt_i32_e64 s[34:35], 28, v0
	v_writelane_b32 v251, s37, 48
	v_cmp_lt_i32_e64 s[36:37], 18, v0
	v_cmp_lt_i32_e64 s[56:57], -1, v0
	v_cmp_lt_i32_e64 s[86:87], 0, v0
	v_writelane_b32 v251, s36, 49
	v_cmp_lt_i32_e64 s[60:61], 1, v0
	v_cmp_lt_i32_e64 s[62:63], 2, v0
	v_writelane_b32 v251, s37, 50
	v_cmp_lt_i32_e64 s[36:37], 23, v0
	v_cmp_lt_i32_e64 s[64:65], 7, v0
	v_cmp_lt_i32_e64 s[66:67], 8, v0
	v_writelane_b32 v251, s36, 51
	v_cmp_lt_i32_e64 s[72:73], 9, v0
	v_lshlrev_b32_e32 v4, 3, v184
	v_writelane_b32 v251, s37, 52
	v_cmp_lt_i32_e64 s[36:37], 24, v0
	v_mul_u32_u24_e32 v3, 0x110, v171
	v_lshlrev_b32_e32 v2, 10, v171
	v_writelane_b32 v251, s36, 53
	s_movk_i32 s52, 0x110
	v_add3_u32 v3, v3, v191, 0
	v_writelane_b32 v251, s37, 54
	v_cmp_lt_i32_e64 s[36:37], 25, v0
	v_lshlrev_b32_e32 v176, 1, v4
	s_mov_b32 s77, 0
	v_writelane_b32 v251, s36, 55
	v_add_u32_e32 v195, 0x4800, v3
	v_add_u32_e32 v198, 0xd400, v3
	v_writelane_b32 v251, s37, 56
	v_cmp_lt_i32_e64 s[36:37], 26, v0
	v_lshlrev_b32_e32 v0, 2, v170
	v_mad_u32_u24 v200, v5, s52, 0
	v_writelane_b32 v251, s36, 57
	v_mad_u32_u24 v201, v171, s52, 0
	s_mov_b64 s[68:69], 0
	v_writelane_b32 v251, s37, 58
	s_add_u32 s36, s90, 0x6200000
	v_writelane_b32 v251, s36, 59
	s_addc_u32 s36, s91, 0
	v_writelane_b32 v251, s36, 60
	s_add_u32 s36, s90, 0x7200000
	v_writelane_b32 v251, s36, 61
	s_addc_u32 s36, s91, 0
	v_writelane_b32 v251, s36, 62
	v_mov_b32_e32 v178, v176
	v_readlane_b32 s36, v251, 16
	s_add_u32 s36, s90, 0x4200000
	v_readlane_b32 s37, v251, 17
	v_readlane_b32 s38, v251, 18
	v_readlane_b32 s39, v251, 19
	v_readlane_b32 s40, v251, 20
	v_readlane_b32 s41, v251, 21
	v_readlane_b32 s42, v251, 22
	v_readlane_b32 s43, v251, 23
	v_readlane_b32 s44, v251, 24
	v_readlane_b32 s45, v251, 25
	v_readlane_b32 s46, v251, 26
	v_readlane_b32 s47, v251, 27
	v_readlane_b32 s48, v251, 28
	v_readlane_b32 s49, v251, 29
	v_readlane_b32 s50, v251, 30
	v_readlane_b32 s51, v251, 31
	v_writelane_b32 v251, s36, 63
	s_addc_u32 s36, s91, 0
	v_writelane_b32 v250, s36, 0
	s_add_u32 s36, s90, 0x6a00000
	v_writelane_b32 v250, s36, 1
	s_addc_u32 s36, s91, 0
	v_writelane_b32 v250, s36, 2
	s_add_u32 s36, s90, 0x7280000
	v_writelane_b32 v250, s36, 3
	s_addc_u32 s36, s91, 0
	v_writelane_b32 v250, s36, 4
	s_add_u32 s36, s90, 0x2000000
	v_writelane_b32 v250, s36, 5
	s_addc_u32 s36, s91, 0
	v_lshl_add_u64 v[172:173], s[40:41], 0, v[0:1]
	v_writelane_b32 v250, s36, 6
	s_add_i32 s40, 0, 0x11800
	s_add_i32 s76, 0, 0x16000
	v_writelane_b32 v250, s40, 7
	v_writelane_b32 v250, s76, 8
	v_writelane_b32 v250, s88, 9
	v_lshl_add_u64 v[174:175], s[42:43], 0, v[0:1]
	v_readlane_b32 s36, v251, 32
	v_writelane_b32 v250, s89, 10
	v_writelane_b32 v250, s90, 11
	v_writelane_b32 v250, s91, 12
	v_add3_u32 v0, v6, v191, 0
	v_mul_u32_u24_e32 v6, 0x90, v171
	v_writelane_b32 v250, s92, 13
	v_lshl_or_b32 v192, s36, 6, v170
	s_movk_i32 s37, 0x90
	v_add3_u32 v196, v6, v191, 0
	v_writelane_b32 v250, s93, 14
	v_add_u32_e32 v193, 0xfffffb80, v192
	v_add_u32_e32 v194, 0x4800, v0
	v_add_u32_e32 v197, 0xd400, v0
	v_add_u32_e32 v199, 0x8c00, v196
	v_mad_u32_u24 v202, v171, s37, 0
	v_mov_b32_e32 v179, v1
	v_lshlrev_b32_e32 v180, 1, v2
	v_mov_b32_e32 v181, v1
	s_mov_b32 s36, 0xf0f0f0f1
	s_movk_i32 s37, 0xffef
	s_movk_i32 s38, 0x490
	s_mov_b32 s39, 0x38e38e39
	v_readlane_b32 s42, v251, 39
	v_writelane_b32 v250, s94, 15
	v_writelane_b32 v250, s95, 16

; #define LAS __attribute__((address_space(3)))
; __device__ __forceinline__ void pool_units(const Ptrs& P, LAS unsigned char* lds, int bx, int G, int tid, int wave, int lane) {
;     unsigned char* ws = P.ws; const int NU = (MTOK / 128) * 4;
;     int u = bx; if (u >= NU) return;
;     u32x4 tv[5]; bf16x8_t wa[2][8]; int gcur = -1;
;     const int r = lane & 31, hh = lane >> 5, rb = wave >> 1;
.LBB9_413:
	s_setprio 0
	v_readlane_b32 s97, v251, 39
	v_readlane_b32 s80, v251, 35
	v_readlane_b32 s22, v251, 33
	s_cmpk_gt_i32 s97, 0x1ff
	v_readlane_b32 s83, v251, 38
	v_readlane_b32 s96, v251, 37
	v_readlane_b32 s81, v251, 36
	v_readlane_b32 s23, v251, 34
	s_cbranch_scc1 .LBB9_444
	s_ashr_i32 s0, s97, 2
	s_lshl_b32 s1, s0, 7
	s_and_b32 s4, s1, 0xf80
	s_add_u32 s14, s90, 0x7300000
	s_addc_u32 s15, s91, 0
	s_ashr_i32 s1, s0, 31
	s_lshl_b64 s[0:1], s[0:1], 17
	s_add_u32 s0, s14, s0
	s_addc_u32 s1, s15, s1
	s_lshl_b32 s3, s97, 8
	s_and_b32 s3, s3, 0x300
	s_add_u32 s0, s0, s3
	v_lshlrev_b32_e32 v0, 3, v208
	v_mov_b32_e32 v117, 0
	s_addc_u32 s1, s1, 0
	s_add_i32 s4, s4, -8
	v_and_b32_e32 v0, 0x78, v0
	v_lshrrev_b32_e32 v134, 4, v208
	v_mov_b32_e32 v34, v117
	v_mov_b32_e32 v35, v117
	v_lshlrev_b32_e32 v118, 1, v0
	v_mov_b32_e32 v119, v117
	v_add_u32_e32 v0, s4, v134
	s_movk_i32 s3, 0x1000
	v_mov_b32_e32 v32, v117
	v_mov_b32_e32 v33, v117
	v_mov_b64_e32 v[38:39], v[34:35]
	s_movk_i32 s2, 0x300
	v_lshl_add_u64 v[4:5], s[0:1], 0, v[118:119]
	v_cmp_gt_u32_e32 vcc, s3, v0
	v_lshlrev_b32_e32 v0, 10, v134
	v_mov_b64_e32 v[36:37], v[32:33]
	s_and_saveexec_b64 s[0:1], vcc
	s_cbranch_execz .LBB9_416
	v_mov_b32_e32 v1, v117
	v_lshl_add_u64 v[2:3], v[4:5], 0, v[0:1]
	v_add_co_u32_e32 v2, vcc, 0xffffe000, v2
	s_nop 1
	v_addc_co_u32_e32 v3, vcc, -1, v3, vcc
	global_load_dwordx4 v[36:39], v[2:3], off nt
